# v79 + leader no longer bumps the unused per-XCC release word
# speedup vs baseline: 1.0056x; 1.0056x over previous
.LBB0_113:
	s_or_b64 exec, exec, s[6:7]
	s_mov_b64 s[6:7], exec
	v_mbcnt_lo_u32_b32 v0, s6, 0
	v_mbcnt_hi_u32_b32 v0, s7, v0
	v_cmp_eq_u32_e32 vcc, 0, v0
	s_waitcnt vmcnt(0)
	buffer_inv sc1
	s_and_saveexec_b64 s[10:11], vcc
	s_cbranch_execz .LBB0_115
	s_bcnt1_i32_b64 s0, s[6:7]
	v_mov_b32_e32 v0, 0x2000
	v_mov_b32_e32 v1, s0
	s_nop 0

.LBB0_249:
	s_or_b64 exec, exec, s[8:9]
	s_mov_b64 s[8:9], exec
	v_mbcnt_lo_u32_b32 v0, s8, 0
	v_mbcnt_hi_u32_b32 v0, s9, v0
	v_cmp_eq_u32_e32 vcc, 0, v0
	s_waitcnt vmcnt(0)
	buffer_inv sc1
	s_and_saveexec_b64 s[10:11], vcc
	s_cbranch_execz .LBB0_251
	s_bcnt1_i32_b64 s0, s[8:9]
	v_mov_b32_e32 v0, 0x2000
	v_mov_b32_e32 v1, s0
	s_nop 0

.LBB0_532:
	s_or_b64 exec, exec, s[10:11]
	s_mov_b64 s[10:11], exec
	v_mbcnt_lo_u32_b32 v0, s10, 0
	v_mbcnt_hi_u32_b32 v0, s11, v0
	v_cmp_eq_u32_e32 vcc, 0, v0
	s_waitcnt vmcnt(0)
	buffer_inv sc1
	s_and_saveexec_b64 s[12:13], vcc
	s_cbranch_execz .LBB0_534
	s_bcnt1_i32_b64 s1, s[10:11]
	v_mov_b32_e32 v0, 0x2000
	v_mov_b32_e32 v1, s1
	s_nop 0

.LBB0_592:
	s_or_b64 exec, exec, s[6:7]
	s_mov_b64 s[6:7], exec
	v_mbcnt_lo_u32_b32 v0, s6, 0
	v_mbcnt_hi_u32_b32 v0, s7, v0
	v_cmp_eq_u32_e32 vcc, 0, v0
	s_waitcnt vmcnt(0)
	buffer_inv sc1
	s_and_saveexec_b64 s[12:13], vcc
	s_cbranch_execz .LBB0_594
	s_bcnt1_i32_b64 s1, s[6:7]
	v_mov_b32_e32 v0, 0x2000
	v_mov_b32_e32 v1, s1
	s_nop 0

.LBB0_969:
	s_or_b64 exec, exec, s[10:11]
	s_mov_b64 s[10:11], exec
	v_mbcnt_lo_u32_b32 v0, s10, 0
	v_mbcnt_hi_u32_b32 v0, s11, v0
	v_cmp_eq_u32_e32 vcc, 0, v0
	s_waitcnt vmcnt(0)
	buffer_inv sc1
	s_and_saveexec_b64 s[12:13], vcc
	s_cbranch_execz .LBB0_971
	s_bcnt1_i32_b64 s0, s[10:11]
	v_mov_b32_e32 v0, 0x2000
	v_mov_b32_e32 v1, s0
	s_nop 0

.LBB0_1041:
	s_or_b64 exec, exec, s[12:13]
	s_mov_b64 s[12:13], exec
	v_mbcnt_lo_u32_b32 v0, s12, 0
	v_mbcnt_hi_u32_b32 v0, s13, v0
	v_cmp_eq_u32_e32 vcc, 0, v0
	s_waitcnt vmcnt(0)
	buffer_inv sc1
	s_and_saveexec_b64 s[14:15], vcc
	s_cbranch_execz .LBB0_1043
	s_bcnt1_i32_b64 s0, s[12:13]
	v_mov_b32_e32 v0, 0x2000
	v_mov_b32_e32 v1, s0
	s_nop 0

.LBB0_1423:
	s_or_b64 exec, exec, s[14:15]
	s_mov_b64 s[14:15], exec
	v_mbcnt_lo_u32_b32 v0, s14, 0
	v_mbcnt_hi_u32_b32 v0, s15, v0
	v_cmp_eq_u32_e32 vcc, 0, v0
	s_waitcnt vmcnt(0)
	buffer_inv sc1
	s_and_saveexec_b64 s[16:17], vcc
	s_cbranch_execz .LBB0_1425
	s_bcnt1_i32_b64 s0, s[14:15]
	v_mov_b32_e32 v0, 0x2000
	v_mov_b32_e32 v1, s0
	s_nop 0

.LBB0_1730:
	s_or_b64 exec, exec, s[14:15]
	s_mov_b64 s[14:15], exec
	v_mbcnt_lo_u32_b32 v0, s14, 0
	v_mbcnt_hi_u32_b32 v0, s15, v0
	v_cmp_eq_u32_e32 vcc, 0, v0
	s_waitcnt vmcnt(0)
	buffer_inv sc1
	s_and_saveexec_b64 s[16:17], vcc
	s_cbranch_execz .LBB0_1732
	s_bcnt1_i32_b64 s1, s[14:15]
	v_mov_b32_e32 v0, 0x2000
	v_mov_b32_e32 v1, s1
	s_nop 0

.LBB0_2125:
	s_or_b64 exec, exec, s[6:7]
	s_mov_b64 s[6:7], exec
	v_mbcnt_lo_u32_b32 v0, s6, 0
	v_mbcnt_hi_u32_b32 v0, s7, v0
	v_cmp_eq_u32_e32 vcc, 0, v0
	s_waitcnt vmcnt(0)
	buffer_inv sc1
	s_and_saveexec_b64 s[8:9], vcc
	s_cbranch_execz .LBB0_2127
	s_bcnt1_i32_b64 s0, s[6:7]
	v_mov_b32_e32 v0, 0x2000
	v_mov_b32_e32 v1, s0
	s_nop 0
